# stick-breaking sample-unit epilogue also in permuted lane order (O permuted in place, permuted load/store addresses), on top of v025
# speedup vs baseline: 1.0228x; 1.0074x over previous
; DEVI unsigned pk_bf16(float lo, float hi) { const f32x2_t v = {lo, hi}; const bf16x2_t b = __builtin_convertvector(v, bf16x2_t); return __builtin_bit_cast(unsigned, b); }
; DEVI float bf_lo(unsigned u) { return __uint_as_float(u << 16); }
; DEVI float bf_hi(unsigned u) { return __uint_as_float(u & 0xffff0000u); }
; DEVI float shx(float v, int m) { return __shfl_xor(v, m); }
; template <int MODE, bool SAMPLE>
; DEVI void attn_unit(const Params& p, const int b, const int h, const int qt, unsigned char* smem) {
;     ...
;     if (active) {
;         const bf16_t* SU = (const bf16_t*)(p.ws + (MODE == 0 ? W_SUA : W_SUB));
;         bf16_t* OAB = (bf16_t*)(p.ws + W_OAB);
; #pragma unroll
;         for (int j = 0; j < 2; ++j) {
;             float inv = 1.0f;
;             if (MODE == 0) { float l = st_l[j]; l += shx(l, 16); l += shx(l, 32); inv = (l > 0.f) ? __builtin_amdgcn_rcpf(l) : 0.f; }
;             const int tok = tok0 + 16 * j + l15;
; #pragma unroll
;             for (int dt = 0; dt < 4; ++dt) {
;                 const int col = h * 64 + 16 * dt + 4 * g;
;                 const u32x2 su = *(const u32x2*)(SU + (size_t)tok * 512 + col);
;                 f32x4 o = O[dt][j] * inv;
;                 u32x2 ov; ov.x = pk_bf16(o[0] * bf_lo(su.x), o[1] * bf_hi(su.x)); ov.y = pk_bf16(o[2] * bf_lo(su.y), o[3] * bf_hi(su.y));
;                 *(u32x2*)(OAB + (MODE == 0 ? (size_t)0 : (size_t)NTOK * 512) + (size_t)tok * 512 + col) = ov;
;             }
;         }
.LBB0_833:
	s_or_b64 exec, exec, s[18:19]
	v_and_b32_e32 v250, 63, v203
	v_and_b32_e32 v251, 3, v250
	v_lshrrev_b32_e32 v252, 4, v250
	v_bfe_u32 v253, v250, 2, 2
	v_lshl_add_u32 v252, v252, 2, v253
	v_lshl_add_u32 v250, v251, 4, v252
	v_lshlrev_b32_e32 v250, 2, v250
	s_and_saveexec_b64 s[0:1], s[12:13]
	s_cbranch_execz .LBB0_809
	v_or_b32_e32 v2, s43, v118
	v_lshl_add_u64 v[0:1], s[24:25], 0, v[68:69]
	v_lshlrev_b32_e32 v64, 1, v2
	v_lshl_add_u64 v[0:1], v[0:1], 0, v[64:65]
	ds_bpermute_b32 v246, v250, v0
	ds_bpermute_b32 v247, v250, v1
	s_waitcnt lgkmcnt(0)
	global_load_dwordx2 v[2:3], v[246:247], off
	global_load_dwordx2 v[4:5], v[246:247], off offset:32
	global_load_dwordx2 v[6:7], v[246:247], off offset:64
	s_nop 0
	global_load_dwordx2 v[0:1], v[246:247], off offset:96
	v_lshl_add_u64 v[8:9], s[24:25], 0, v[70:71]
	v_lshl_add_u64 v[8:9], v[8:9], 0, v[64:65]
	ds_bpermute_b32 v248, v250, v8
	ds_bpermute_b32 v249, v250, v9
	s_waitcnt lgkmcnt(0)
	global_load_dwordx2 v[10:11], v[248:249], off
	global_load_dwordx2 v[12:13], v[248:249], off offset:32
	global_load_dwordx2 v[14:15], v[248:249], off offset:64
	s_nop 0
	global_load_dwordx2 v[8:9], v[248:249], off offset:96
	v_lshl_add_u64 v[48:49], s[26:27], 0, v[68:69]
	v_lshl_add_u64 v[50:51], s[26:27], 0, v[70:71]
	v_lshl_add_u64 v[48:49], v[48:49], 0, v[64:65]
	v_lshl_add_u64 v[50:51], v[50:51], 0, v[64:65]
	ds_bpermute_b32 v16, v250, v16
	ds_bpermute_b32 v17, v250, v17
	ds_bpermute_b32 v18, v250, v18
	ds_bpermute_b32 v19, v250, v19
	ds_bpermute_b32 v20, v250, v20
	ds_bpermute_b32 v21, v250, v21
	ds_bpermute_b32 v22, v250, v22
	ds_bpermute_b32 v23, v250, v23
	ds_bpermute_b32 v24, v250, v24
	ds_bpermute_b32 v25, v250, v25
	ds_bpermute_b32 v26, v250, v26
	s_waitcnt lgkmcnt(0)
	ds_bpermute_b32 v27, v250, v27
	ds_bpermute_b32 v28, v250, v28
	ds_bpermute_b32 v29, v250, v29
	ds_bpermute_b32 v30, v250, v30
	ds_bpermute_b32 v31, v250, v31
	ds_bpermute_b32 v32, v250, v32
	ds_bpermute_b32 v33, v250, v33
	ds_bpermute_b32 v34, v250, v34
	ds_bpermute_b32 v35, v250, v35
	ds_bpermute_b32 v36, v250, v36
	ds_bpermute_b32 v37, v250, v37
	s_waitcnt lgkmcnt(0)
	ds_bpermute_b32 v38, v250, v38
	ds_bpermute_b32 v39, v250, v39
	ds_bpermute_b32 v40, v250, v40
	ds_bpermute_b32 v41, v250, v41
	ds_bpermute_b32 v42, v250, v42
	ds_bpermute_b32 v43, v250, v43
	ds_bpermute_b32 v44, v250, v44
	ds_bpermute_b32 v45, v250, v45
	ds_bpermute_b32 v46, v250, v46
	ds_bpermute_b32 v47, v250, v47
	s_waitcnt lgkmcnt(0)
	s_waitcnt vmcnt(7)
	v_lshlrev_b32_e32 v52, 16, v2
	v_and_b32_e32 v53, 0xffff0000, v2
	v_lshlrev_b32_e32 v2, 16, v3
	v_and_b32_e32 v3, 0xffff0000, v3
	s_waitcnt vmcnt(6)
	v_lshlrev_b32_e32 v54, 16, v4
	v_and_b32_e32 v55, 0xffff0000, v4
	v_lshlrev_b32_e32 v4, 16, v5
	v_and_b32_e32 v5, 0xffff0000, v5
	s_waitcnt vmcnt(5)
	v_lshlrev_b32_e32 v56, 16, v6
	v_and_b32_e32 v57, 0xffff0000, v6
	v_lshlrev_b32_e32 v6, 16, v7
	v_and_b32_e32 v7, 0xffff0000, v7
	s_waitcnt vmcnt(4)
	v_lshlrev_b32_e32 v58, 16, v0
	v_and_b32_e32 v59, 0xffff0000, v0
	v_lshlrev_b32_e32 v0, 16, v1
	v_and_b32_e32 v1, 0xffff0000, v1
	s_waitcnt vmcnt(3)
	v_lshlrev_b32_e32 v60, 16, v10
	v_and_b32_e32 v61, 0xffff0000, v10
	v_lshlrev_b32_e32 v10, 16, v11
	v_and_b32_e32 v11, 0xffff0000, v11
	s_waitcnt vmcnt(2)
	v_lshlrev_b32_e32 v62, 16, v12
	v_and_b32_e32 v63, 0xffff0000, v12
	v_lshlrev_b32_e32 v12, 16, v13
	v_and_b32_e32 v13, 0xffff0000, v13
	s_waitcnt vmcnt(1)
	v_lshlrev_b32_e32 v68, 16, v14
	v_and_b32_e32 v69, 0xffff0000, v14
	v_lshlrev_b32_e32 v14, 16, v15
	v_and_b32_e32 v15, 0xffff0000, v15
	v_pk_mul_f32 v[24:25], v[24:25], v[52:53]
	v_pk_mul_f32 v[2:3], v[26:27], v[2:3]
	v_pk_mul_f32 v[4:5], v[34:35], v[4:5]
	v_pk_mul_f32 v[6:7], v[42:43], v[6:7]
	v_pk_mul_f32 v[0:1], v[46:47], v[0:1]
	v_pk_mul_f32 v[16:17], v[16:17], v[60:61]
	v_pk_mul_f32 v[10:11], v[18:19], v[10:11]
	s_waitcnt vmcnt(0)
	v_lshlrev_b32_e32 v70, 16, v8
	v_and_b32_e32 v71, 0xffff0000, v8
	v_lshlrev_b32_e32 v8, 16, v9
	v_and_b32_e32 v9, 0xffff0000, v9
	v_pk_mul_f32 v[26:27], v[32:33], v[54:55]
	v_pk_mul_f32 v[32:33], v[40:41], v[56:57]
	v_pk_mul_f32 v[34:35], v[44:45], v[58:59]
	v_pk_mul_f32 v[18:19], v[28:29], v[62:63]
	v_pk_mul_f32 v[12:13], v[30:31], v[12:13]
	v_pk_mul_f32 v[28:29], v[36:37], v[68:69]
	v_pk_mul_f32 v[14:15], v[38:39], v[14:15]
	v_cvt_pk_bf16_f32 v24, v24, v25
	v_cvt_pk_bf16_f32 v25, v2, v3
	v_cvt_pk_bf16_f32 v3, v4, v5
	v_cvt_pk_bf16_f32 v5, v6, v7
	v_cvt_pk_bf16_f32 v7, v0, v1
	v_cvt_pk_bf16_f32 v0, v16, v17
	v_cvt_pk_bf16_f32 v1, v10, v11
	v_pk_mul_f32 v[20:21], v[20:21], v[70:71]
	v_cvt_pk_bf16_f32 v2, v26, v27
	v_cvt_pk_bf16_f32 v4, v32, v33
	v_cvt_pk_bf16_f32 v6, v34, v35
	v_cvt_pk_bf16_f32 v10, v18, v19
	v_cvt_pk_bf16_f32 v11, v12, v13
	v_cvt_pk_bf16_f32 v12, v28, v29
	v_cvt_pk_bf16_f32 v13, v14, v15
	ds_bpermute_b32 v246, v250, v48
	ds_bpermute_b32 v247, v250, v49
	s_waitcnt lgkmcnt(0)
	global_store_dwordx2 v[246:247], v[24:25], off
	global_store_dwordx2 v[246:247], v[2:3], off offset:32
	global_store_dwordx2 v[246:247], v[4:5], off offset:64
	global_store_dwordx2 v[246:247], v[6:7], off offset:96
	ds_bpermute_b32 v248, v250, v50
	ds_bpermute_b32 v249, v250, v51
	s_waitcnt lgkmcnt(0)
	global_store_dwordx2 v[248:249], v[0:1], off
	global_store_dwordx2 v[248:249], v[10:11], off offset:32
	global_store_dwordx2 v[248:249], v[12:13], off offset:64
	v_pk_mul_f32 v[0:1], v[22:23], v[8:9]
	v_cvt_pk_bf16_f32 v14, v20, v21
	v_cvt_pk_bf16_f32 v15, v0, v1
	global_store_dwordx2 v[248:249], v[14:15], off offset:96
	s_branch .LBB0_809
